# mix: the three stage_tile weight-staging loops (4 serialized load->vmcnt(0)->ds_write iterations each) unrolled to 4 loads in flight with counted waits
# speedup vs baseline: 1.0040x; 1.0040x over previous
; __device__ __forceinline__ void stage_tile(unsigned char* dst, const bf16_t* src, int ld) {
;     for (int idx = threadIdx.x; idx < 2048; idx += 512) { const int row = idx >> 4, ch = idx & 15;
;         *(u32x4*)(dst + swz(row, ch)) = *(const u32x4*)(src + (size_t)row * ld + ch * 8); }
; __device__ void phase_mix(const Params& p, unsigned char* smem) {
;     ...
;     stage_tile(Bs, (const bf16_t*)(p.ws + OFF_WPT) + g * 16384, 128);
;     const int tstep = gridDim.x >> 2, tlim = (REP_PH == 2 ? 1024 : 512);
;     ...
;     {
;         const int left = 1 << g, right = (1 << g) - 1;
;         u32x4 hreg[5];
;     ...
;         HLOAD(blockIdx.x >> 2);
.LBB0_131:
	v_xor_b32_e32 v5, v3, v4
	v_lshlrev_b32_e32 v5, 4, v5
	v_and_b32_e32 v5, 0xf0, v5
	v_add_u32_e32 v5, v2, v5
	v_lshl_add_u64 v[24:25], v[0:1], 0, s[4:5]
	v_lshl_add_u64 v[26:27], v[24:25], 0, s[4:5]
	v_lshl_add_u64 v[28:29], v[26:27], 0, s[4:5]
	global_load_dwordx4 v[6:9], v[0:1], off
	global_load_dwordx4 v[12:15], v[24:25], off
	global_load_dwordx4 v[16:19], v[26:27], off
	global_load_dwordx4 v[20:23], v[28:29], off
	s_waitcnt vmcnt(3)
	ds_write_b128 v5, v[6:9]
	s_waitcnt vmcnt(2)
	ds_write_b128 v5, v[12:15] offset:8192
	s_waitcnt vmcnt(1)
	ds_write_b128 v5, v[16:19] offset:16384
	s_waitcnt vmcnt(0)
	ds_write_b128 v5, v[20:23] offset:24576
	s_or_b64 exec, exec, s[0:1]
	s_lshl_b32 s0, s2, 5
	s_and_b32 s26, s0, 0xff80
	s_cmpk_lt_u32 s26, 0x8000
	s_movk_i32 s1, 0xf80
	s_cselect_b32 s1, s1, 0x780
	s_movk_i32 s3, 0x1000
	s_cselect_b32 s25, s3, 0x800
	s_and_b32 s27, s1, s0
	s_sub_i32 s3, s26, s27
	s_add_i32 s12, s27, -8
	s_lshl_b32 s0, s14, 8
	v_ashrrev_i32_e32 v84, 4, v94
	s_add_u32 s20, s78, s0
	v_add_u32_e32 v5, s12, v84
	s_movk_i32 s0, 0x900
	v_lshlrev_b32_e32 v20, 4, v94
	v_mov_b32_e32 v4, 0
	v_cmp_gt_i32_e64 s[4:5], s0, v94
	v_cmp_gt_i32_e64 s[0:1], s25, v5
	s_addc_u32 s21, s79, 0
	v_and_b32_e32 v0, 0xf0, v20
	v_mov_b32_e32 v1, v4
	v_cmp_lt_i32_e32 vcc, -1, v5
	s_and_b64 s[0:1], s[4:5], s[0:1]
	v_lshl_add_u64 v[42:43], s[20:21], 0, v[0:1]
	s_and_b64 s[6:7], s[0:1], vcc
	v_mov_b32_e32 v0, 0
	v_mov_b32_e32 v1, 0
	v_mov_b32_e32 v2, 0
	v_mov_b32_e32 v3, 0
	s_and_saveexec_b64 s[0:1], s[6:7]
	s_cbranch_execz .LBB0_134
	v_add_u32_e32 v0, s3, v5
	s_movk_i32 s6, 0x1800
	v_mad_i64_i32 v[0:1], s[6:7], v0, s6, v[42:43]
	global_load_dwordx4 v[0:3], v[0:1], off

; __device__ void phase_mix(const Params& p, unsigned char* smem) {
;     ...
;         stage_tile(Bs, (const bf16_t*)(p.ws + OFF_WQT) + h * 16384, 128);
;         stage_tile(B2s, (const bf16_t*)(p.ws + OFF_WKT) + h * 16384, 128);
;         const int ch = tid & 15, cc = h * 128 + ch * 8;
;         float cw[3][8], cb[8];
; #pragma unroll
;         for (int e = 0; e < 8; ++e) { cb[e] = p.conv_b[cc + e];
; #pragma unroll
;             for (int j = 0; j < 3; ++j) cw[j][e] = p.conv_w[j * 512 + cc + e]; }
;         u32x4 creg[4][3];
;     ...
;         CLOAD(blockIdx.x >> 2);
.LBB0_170:
	v_xor_b32_e32 v8, v2, v3
	v_lshlrev_b32_e32 v8, 4, v8
	v_and_b32_e32 v8, 0xf0, v8
	v_add_u32_e32 v8, v71, v8
	v_lshl_add_u64 v[24:25], v[0:1], 0, s[4:5]
	v_lshl_add_u64 v[26:27], v[24:25], 0, s[4:5]
	v_lshl_add_u64 v[28:29], v[26:27], 0, s[4:5]
	global_load_dwordx4 v[4:7], v[0:1], off
	global_load_dwordx4 v[12:15], v[24:25], off
	global_load_dwordx4 v[16:19], v[26:27], off
	global_load_dwordx4 v[20:23], v[28:29], off
	s_waitcnt vmcnt(3)
	ds_write_b128 v8, v[4:7]
	s_waitcnt vmcnt(2)
	ds_write_b128 v8, v[12:15] offset:8192
	s_waitcnt vmcnt(1)
	ds_write_b128 v8, v[16:19] offset:16384
	s_waitcnt vmcnt(0)
	ds_write_b128 v8, v[20:23] offset:24576
	v_add_u32_e32 v71, 0x8000, v71
	s_or_b64 exec, exec, s[0:1]
	s_mov_b64 s[0:1], 0x18fc0000
	v_add_u32_e32 v2, 0x10000, v70
	v_lshl_add_u64 v[0:1], v[40:41], 0, s[0:1]
	s_mov_b64 s[0:1], 0
	s_mov_b64 s[4:5], 0x2000
	s_movk_i32 s6, 0x5ff
	v_mov_b32_e32 v3, v170
	v_mov_b32_e32 v4, v176
.LBB0_172:
	v_xor_b32_e32 v5, v3, v4
	v_lshlrev_b32_e32 v5, 4, v5
	v_and_b32_e32 v5, 0xf0, v5
	v_add_u32_e32 v5, v2, v5
	v_lshl_add_u64 v[24:25], v[0:1], 0, s[4:5]
	v_lshl_add_u64 v[26:27], v[24:25], 0, s[4:5]
	v_lshl_add_u64 v[28:29], v[26:27], 0, s[4:5]
	global_load_dwordx4 v[6:9], v[0:1], off
	global_load_dwordx4 v[12:15], v[24:25], off
	global_load_dwordx4 v[16:19], v[26:27], off
	global_load_dwordx4 v[20:23], v[28:29], off
	s_waitcnt vmcnt(3)
	ds_write_b128 v5, v[6:9]
	s_waitcnt vmcnt(2)
	ds_write_b128 v5, v[12:15] offset:8192
	s_waitcnt vmcnt(1)
	ds_write_b128 v5, v[16:19] offset:16384
	s_waitcnt vmcnt(0)
	ds_write_b128 v5, v[20:23] offset:24576
	s_or_b64 exec, exec, s[0:1]
	v_lshl_or_b32 v33, v96, 3, s28
	v_mov_b32_e32 v32, 0
	v_readlane_b32 s36, v254, 0
	v_lshlrev_b32_e32 v24, 2, v33
	v_mov_b32_e32 v25, v32
	v_readlane_b32 s46, v254, 10
	v_readlane_b32 s47, v254, 11
	v_readlane_b32 s48, v254, 12
	v_readlane_b32 s49, v254, 13
	v_lshl_add_u64 v[26:27], s[46:47], 0, v[24:25]
	s_nop 3
	global_load_dwordx4 v[0:3], v24, s[48:49] offset:16
	global_load_dwordx4 v[4:7], v24, s[46:47] offset:16
	global_load_dwordx4 v[8:11], v24, s[48:49]
	global_load_dwordx4 v[12:15], v24, s[46:47]
	global_load_dwordx4 v[16:19], v24, s[46:47] offset:2064
	global_load_dwordx4 v[20:23], v24, s[46:47] offset:2048
	s_mov_b64 s[0:1], 0x1000
	v_lshl_add_u64 v[28:29], v[26:27], 0, s[0:1]
	s_movk_i32 s0, 0x1000
	v_add_co_u32_e32 v24, vcc, s0, v26
	s_add_i32 s6, s27, -1
	s_nop 0
	v_addc_co_u32_e32 v25, vcc, 0, v27, vcc
	global_load_dwordx4 v[24:27], v[24:25], off
	s_nop 0
	global_load_dwordx4 v[28:31], v[28:29], off offset:16
	s_add_u32 s4, s26, -1
	v_add_u32_e32 v40, s6, v84
	s_addc_u32 s5, 0, -1
	v_ashrrev_i32_e32 v85, 31, v84
	v_cmp_lt_i32_e32 vcc, -1, v40
	v_cmp_gt_i32_e64 s[0:1], s25, v40
	v_lshl_add_u64 v[42:43], s[4:5], 0, v[84:85]
	s_and_b64 s[8:9], vcc, s[0:1]
	v_lshlrev_b32_e32 v86, 1, v33
	v_mov_b32_e32 v36, 0
	v_mov_b32_e32 v37, 0
	v_mov_b32_e32 v38, 0
	v_mov_b32_e32 v39, 0
	v_readlane_b32 s37, v254, 1
	v_readlane_b32 s38, v254, 2
	v_readlane_b32 s39, v254, 3
	v_readlane_b32 s40, v254, 4
	v_readlane_b32 s41, v254, 5
	v_readlane_b32 s42, v254, 6
	v_readlane_b32 s43, v254, 7
	v_readlane_b32 s44, v254, 8
	v_readlane_b32 s45, v254, 9
	v_readlane_b32 s50, v254, 14
	v_readlane_b32 s51, v254, 15
	s_and_saveexec_b64 s[0:1], s[8:9]
	s_cbranch_execz .LBB0_175
	s_movk_i32 s7, 0x1800
	v_mov_b64_e32 v[34:35], s[78:79]
	v_mad_i64_i32 v[34:35], s[8:9], v42, s7, v[34:35]
	v_mov_b32_e32 v87, 0
	v_lshl_add_u64 v[34:35], v[34:35], 0, v[86:87]
	global_load_dwordx4 v[36:39], v[34:35], off offset:2048
